# v33 + non-temporal stores for the split-K partial-sum slabs of layer 0 (written once, read once by the next norm)
# baseline (speedup 1.0000x reference)
.LBB0_79:
	v_mov_b32_e32 v148, v185
	v_mov_b32_e32 v76, v187
	s_cmp_eq_u32 s0, 0
	s_cbranch_scc1 .LBB0_81
	s_add_i32 s48, s0, -1
	s_ashr_i32 s27, s26, 31
	s_lshl_b64 s[0:1], s[48:49], 23
	s_add_u32 s2, s65, s0
	s_addc_u32 s4, s76, s1
	s_lshl_b64 s[0:1], s[26:27], 20
	s_add_u32 s2, s2, s0
	s_addc_u32 s4, s4, s1
	s_lshl_b32 s0, s28, 8
	s_ashr_i32 s1, s0, 31
	s_lshl_b64 s[0:1], s[0:1], 2
	s_add_u32 s0, s2, s0
	s_addc_u32 s1, s4, s1
	v_mov_b32_e32 v77, v148
	s_add_u32 s0, s0, s96
	v_lshlrev_b32_e32 v78, 2, v76
	s_addc_u32 s1, s1, 0
	v_add_u32_e32 v84, s82, v77
	v_ashrrev_i32_e32 v79, 31, v78
	v_ashrrev_i32_e32 v85, 31, v84
	v_lshl_add_u64 v[78:79], v[78:79], 2, s[0:1]
	v_lshlrev_b64 v[84:85], 12, v[84:85]
	v_lshl_add_u64 v[84:85], v[78:79], 0, v[84:85]
	global_store_dwordx4 v[84:85], v[144:147], off nt
	global_store_dwordx4 v[84:85], v[140:143], off offset:64 nt
	global_store_dwordx4 v[84:85], v[128:131], off offset:512 nt
	global_store_dwordx4 v[84:85], v[124:127], off offset:576 nt
	v_mov_b32_e32 v77, v148
	s_nop 0
	v_add_u32_e32 v84, s86, v77
	v_ashrrev_i32_e32 v85, 31, v84
	v_lshlrev_b64 v[84:85], 12, v[84:85]
	v_lshl_add_u64 v[84:85], v[78:79], 0, v[84:85]
	global_store_dwordx4 v[84:85], v[136:139], off nt
	global_store_dwordx4 v[84:85], v[132:135], off offset:64 nt
	global_store_dwordx4 v[84:85], v[120:123], off offset:512 nt
	global_store_dwordx4 v[84:85], v[116:119], off offset:576 nt
	v_mov_b32_e32 v77, v148
	s_nop 0
	v_add_u32_e32 v84, s87, v77
	v_ashrrev_i32_e32 v85, 31, v84
	v_lshlrev_b64 v[84:85], 12, v[84:85]
	v_lshl_add_u64 v[84:85], v[78:79], 0, v[84:85]
	global_store_dwordx4 v[84:85], v[108:111], off nt
	global_store_dwordx4 v[84:85], v[104:107], off offset:64 nt
	global_store_dwordx4 v[84:85], v[88:91], off offset:512 nt
	global_store_dwordx4 v[84:85], v[80:83], off offset:576 nt
	v_mov_b32_e32 v77, v148
	s_nop 0
	v_add_u32_e32 v84, s88, v77
	v_ashrrev_i32_e32 v85, 31, v84
	v_lshlrev_b64 v[84:85], 12, v[84:85]
	v_lshl_add_u64 v[84:85], v[78:79], 0, v[84:85]
	global_store_dwordx4 v[84:85], v[100:103], off nt
	global_store_dwordx4 v[84:85], v[92:95], off offset:64 nt
	global_store_dwordx4 v[84:85], v[72:75], off offset:512 nt
	global_store_dwordx4 v[84:85], v[68:71], off offset:576 nt
	v_mov_b32_e32 v77, v148
	s_nop 0
	v_add_u32_e32 v84, s89, v77
	v_ashrrev_i32_e32 v85, 31, v84
	v_lshlrev_b64 v[84:85], 12, v[84:85]
	v_lshl_add_u64 v[84:85], v[78:79], 0, v[84:85]
	global_store_dwordx4 v[84:85], v[64:67], off nt
	global_store_dwordx4 v[84:85], v[60:63], off offset:64 nt
	global_store_dwordx4 v[84:85], v[48:51], off offset:512 nt
	global_store_dwordx4 v[84:85], v[44:47], off offset:576 nt
	v_mov_b32_e32 v77, v148
	s_nop 0
	v_add_u32_e32 v84, s90, v77
	v_ashrrev_i32_e32 v85, 31, v84
	v_lshlrev_b64 v[84:85], 12, v[84:85]
	v_lshl_add_u64 v[84:85], v[78:79], 0, v[84:85]
	global_store_dwordx4 v[84:85], v[56:59], off nt
	global_store_dwordx4 v[84:85], v[52:55], off offset:64 nt
	global_store_dwordx4 v[84:85], v[40:43], off offset:512 nt
	global_store_dwordx4 v[84:85], v[36:39], off offset:576 nt
	v_mov_b32_e32 v77, v148
	s_nop 0
	v_add_u32_e32 v84, s91, v77
	v_ashrrev_i32_e32 v85, 31, v84
	v_lshlrev_b64 v[84:85], 12, v[84:85]
	v_lshl_add_u64 v[84:85], v[78:79], 0, v[84:85]
	global_store_dwordx4 v[84:85], v[32:35], off nt
	global_store_dwordx4 v[84:85], v[28:31], off offset:64 nt
	global_store_dwordx4 v[84:85], v[24:27], off offset:512 nt
	global_store_dwordx4 v[84:85], v[20:23], off offset:576 nt
	v_mov_b32_e32 v77, v148
	s_nop 0
	v_add_u32_e32 v84, s92, v77
	v_ashrrev_i32_e32 v85, 31, v84
	v_lshlrev_b64 v[84:85], 12, v[84:85]
	v_lshl_add_u64 v[78:79], v[78:79], 0, v[84:85]
	global_store_dwordx4 v[78:79], v[16:19], off nt
	global_store_dwordx4 v[78:79], v[12:15], off offset:64 nt
	global_store_dwordx4 v[78:79], v[8:11], off offset:512 nt
	global_store_dwordx4 v[78:79], v[4:7], off offset:576 nt
	s_cbranch_execz .LBB0_82
	s_branch .LBB0_90

.LBB0_303:
	v_mov_b32_e32 v148, v185
	v_mov_b32_e32 v100, v187
	s_cmp_eq_u32 s0, 0
	s_cbranch_scc1 .LBB0_305
	s_add_i32 s48, s0, -1
	s_ashr_i32 s29, s28, 31
	s_lshl_b64 s[0:1], s[48:49], 23
	s_add_u32 s2, s76, s0
	s_addc_u32 s4, s82, s1
	s_lshl_b64 s[0:1], s[28:29], 20
	s_add_u32 s2, s2, s0
	s_addc_u32 s4, s4, s1
	s_lshl_b32 s0, s30, 8
	s_ashr_i32 s1, s0, 31
	s_lshl_b64 s[0:1], s[0:1], 2
	s_add_u32 s0, s2, s0
	s_addc_u32 s1, s4, s1
	v_mov_b32_e32 v101, v148
	s_add_u32 s0, s0, s97
	v_lshlrev_b32_e32 v102, 2, v100
	s_addc_u32 s1, s1, 0
	v_add_u32_e32 v104, s83, v101
	v_ashrrev_i32_e32 v103, 31, v102
	v_ashrrev_i32_e32 v105, 31, v104
	v_lshl_add_u64 v[102:103], v[102:103], 2, s[0:1]
	v_lshlrev_b64 v[104:105], 12, v[104:105]
	v_lshl_add_u64 v[104:105], v[102:103], 0, v[104:105]
	global_store_dwordx4 v[104:105], v[144:147], off nt
	global_store_dwordx4 v[104:105], v[140:143], off offset:64 nt
	global_store_dwordx4 v[104:105], v[124:127], off offset:512 nt
	global_store_dwordx4 v[104:105], v[120:123], off offset:576 nt
	v_mov_b32_e32 v101, v148
	s_nop 0
	v_add_u32_e32 v104, s87, v101
	v_ashrrev_i32_e32 v105, 31, v104
	v_lshlrev_b64 v[104:105], 12, v[104:105]
	v_lshl_add_u64 v[104:105], v[102:103], 0, v[104:105]
	global_store_dwordx4 v[104:105], v[136:139], off nt
	global_store_dwordx4 v[104:105], v[132:135], off offset:64 nt
	global_store_dwordx4 v[104:105], v[116:119], off offset:512 nt
	global_store_dwordx4 v[104:105], v[112:115], off offset:576 nt
	v_mov_b32_e32 v101, v148
	s_nop 0
	v_add_u32_e32 v104, s88, v101
	v_ashrrev_i32_e32 v105, 31, v104
	v_lshlrev_b64 v[104:105], 12, v[104:105]
	v_lshl_add_u64 v[104:105], v[102:103], 0, v[104:105]
	global_store_dwordx4 v[104:105], v[96:99], off nt
	global_store_dwordx4 v[104:105], v[92:95], off offset:64 nt
	global_store_dwordx4 v[104:105], v[80:83], off offset:512 nt
	global_store_dwordx4 v[104:105], v[76:79], off offset:576 nt
	v_mov_b32_e32 v101, v148
	s_nop 0
	v_add_u32_e32 v104, s89, v101
	v_ashrrev_i32_e32 v105, 31, v104
	v_lshlrev_b64 v[104:105], 12, v[104:105]
	v_lshl_add_u64 v[104:105], v[102:103], 0, v[104:105]
	global_store_dwordx4 v[104:105], v[88:91], off nt
	global_store_dwordx4 v[104:105], v[84:87], off offset:64 nt
	global_store_dwordx4 v[104:105], v[72:75], off offset:512 nt
	global_store_dwordx4 v[104:105], v[68:71], off offset:576 nt
	v_mov_b32_e32 v101, v148
	s_nop 0
	v_add_u32_e32 v104, s90, v101
	v_ashrrev_i32_e32 v105, 31, v104
	v_lshlrev_b64 v[104:105], 12, v[104:105]
	v_lshl_add_u64 v[104:105], v[102:103], 0, v[104:105]
	global_store_dwordx4 v[104:105], v[64:67], off nt
	global_store_dwordx4 v[104:105], v[60:63], off offset:64 nt
	global_store_dwordx4 v[104:105], v[48:51], off offset:512 nt
	global_store_dwordx4 v[104:105], v[44:47], off offset:576 nt
	v_mov_b32_e32 v101, v148
	s_nop 0
	v_add_u32_e32 v104, s91, v101
	v_ashrrev_i32_e32 v105, 31, v104
	v_lshlrev_b64 v[104:105], 12, v[104:105]
	v_lshl_add_u64 v[104:105], v[102:103], 0, v[104:105]
	global_store_dwordx4 v[104:105], v[56:59], off nt
	global_store_dwordx4 v[104:105], v[52:55], off offset:64 nt
	global_store_dwordx4 v[104:105], v[40:43], off offset:512 nt
	global_store_dwordx4 v[104:105], v[36:39], off offset:576 nt
	v_mov_b32_e32 v101, v148
	s_nop 0
	v_add_u32_e32 v104, s92, v101
	v_ashrrev_i32_e32 v105, 31, v104
	v_lshlrev_b64 v[104:105], 12, v[104:105]
	v_lshl_add_u64 v[104:105], v[102:103], 0, v[104:105]
	global_store_dwordx4 v[104:105], v[32:35], off nt
	global_store_dwordx4 v[104:105], v[28:31], off offset:64 nt
	global_store_dwordx4 v[104:105], v[20:23], off offset:512 nt
	global_store_dwordx4 v[104:105], v[16:19], off offset:576 nt
	v_mov_b32_e32 v101, v148
	s_nop 0
	v_add_u32_e32 v104, s93, v101
	v_ashrrev_i32_e32 v105, 31, v104
	v_lshlrev_b64 v[104:105], 12, v[104:105]
	v_lshl_add_u64 v[102:103], v[102:103], 0, v[104:105]
	global_store_dwordx4 v[102:103], v[24:27], off nt
	global_store_dwordx4 v[102:103], v[12:15], off offset:64 nt
	global_store_dwordx4 v[102:103], v[8:11], off offset:512 nt
	global_store_dwordx4 v[102:103], v[4:7], off offset:576 nt
	s_cbranch_execz .LBB0_306
	s_branch .LBB0_310
